# mLSTM S tiles: the 16 cumulative-gate values per tile fetched with four ds_read_b128 behind the first fragment reads instead of four exposed 3-4 dword round trips; waits re-derived per consumer
# speedup vs baseline: 1.0009x; 1.0009x over previous
.LBB0_1700:
	v_or_b32_e32 v4, s58, v101
	v_mad_u32_u24 v13, v4, s68, v0
	ds_read_b128 v[4:7], v13 offset:18432
	ds_read_b128 v[32:35], v2
	ds_read_b128 v[102:105], v2 offset:32
	ds_read_b128 v[106:109], v13 offset:18464
	v_add_u32_e32 v176, s58, v3
	v_lshl_add_u32 v176, v176, 2, v93
	ds_read_b128 v[160:163], v176
	ds_read_b128 v[164:167], v176 offset:32
	ds_read_b128 v[168:171], v176 offset:64
	ds_read_b128 v[172:175], v176 offset:96
	s_waitcnt lgkmcnt(6)
	v_mfma_f32_32x32x16_bf16 v[32:47], v[4:7], v[32:35], 0
	s_waitcnt lgkmcnt(4)
	v_mfma_f32_32x32x16_bf16 v[32:47], v[106:109], v[102:105], v[32:47]
	ds_read_b128 v[4:7], v13 offset:18496
	ds_read_b128 v[102:105], v2 offset:64
	ds_read_b128 v[106:109], v13 offset:18528
	ds_read_b128 v[110:113], v2 offset:96
	v_mov_b32_e32 v13, 0
	s_waitcnt lgkmcnt(2)
	v_mfma_f32_32x32x16_bf16 v[32:47], v[4:7], v[102:105], v[32:47]
	v_add_u32_e32 v103, s58, v3
	v_lshl_add_u32 v15, v103, 2, v93
	s_waitcnt lgkmcnt(4)
	v_mov_b32_e32 v4, v161
	v_mov_b32_e32 v5, v162
	v_mov_b32_e32 v6, v163
	v_cmp_le_i32_e32 vcc, v103, v10
	v_mov_b32_e32 v102, 0
	s_waitcnt lgkmcnt(0)
	v_mfma_f32_32x32x16_bf16 v[32:47], v[106:109], v[110:113], v[32:47]
	s_and_saveexec_b64 s[10:11], vcc
	s_cbranch_execz .LBB0_1702
	v_mov_b32_e32 v7, v160
	s_nop 0
	v_add_f32_e32 v7, v11, v7
	v_mul_f32_e32 v7, 0x3fb8aa3b, v7
	v_exp_f32_e32 v7, v7
	s_nop 4
	v_mul_f32_e32 v102, v32, v7
.LBB0_1702:
	s_or_b64 exec, exec, s[10:11]
	s_nop 0
	v_add_f32_e32 v4, v11, v4
	v_mul_f32_e32 v4, 0x3fb8aa3b, v4
	v_exp_f32_e32 v4, v4
	v_add_f32_e32 v5, v11, v5
	v_mul_f32_e32 v5, 0x3fb8aa3b, v5
	s_nop 0
	v_add_f32_e32 v6, v11, v6
	v_exp_f32_e32 v5, v5
	v_mul_f32_e32 v6, 0x3fb8aa3b, v6
	v_exp_f32_e32 v6, v6
	v_mul_f32_e32 v4, v33, v4
	v_cmp_lt_i32_e32 vcc, v103, v10
	v_mul_f32_e32 v5, v34, v5
	v_lshl_add_u32 v14, v103, 1, v12
	v_cndmask_b32_e32 v32, 0, v4, vcc
	v_or_b32_e32 v4, 2, v103
	v_cmp_le_i32_e32 vcc, v4, v10
	v_or_b32_e32 v4, 3, v103
	s_nop 0
	v_cndmask_b32_e32 v33, 0, v5, vcc
	v_mul_f32_e32 v5, v35, v6
	v_cmp_le_i32_e32 vcc, v4, v10
	v_cvt_pk_bf16_f32 v4, v102, v32
	v_add_u32_e32 v6, 8, v103
	v_mov_b32_e32 v35, 0
	v_cndmask_b32_e32 v34, 0, v5, vcc
	v_cvt_pk_bf16_f32 v5, v33, v34
	ds_write_b64 v14, v[4:5]
	v_mov_b32_e32 v4, v165
	v_mov_b32_e32 v5, v166
	v_mov_b32_e32 v7, v167
	v_cmp_le_i32_e32 vcc, v6, v10
	s_and_saveexec_b64 s[10:11], vcc
	s_cbranch_execz .LBB0_1704
	v_mov_b32_e32 v35, v164
	s_nop 0
	v_add_f32_e32 v35, v11, v35
	v_mul_f32_e32 v35, 0x3fb8aa3b, v35
	v_exp_f32_e32 v35, v35
	s_nop 0
	v_mul_f32_e32 v35, v36, v35
.LBB0_1704:
	s_or_b64 exec, exec, s[10:11]
	s_nop 0
	v_add_f32_e32 v4, v11, v4
	v_mul_f32_e32 v4, 0x3fb8aa3b, v4
	v_exp_f32_e32 v4, v4
	v_add_f32_e32 v5, v11, v5
	v_mul_f32_e32 v5, 0x3fb8aa3b, v5
	s_nop 0
	v_add_f32_e32 v7, v11, v7
	v_exp_f32_e32 v5, v5
	v_mul_f32_e32 v7, 0x3fb8aa3b, v7
	v_exp_f32_e32 v7, v7
	v_mul_f32_e32 v4, v37, v4
	v_cmp_lt_i32_e32 vcc, v6, v10
	v_mul_f32_e32 v5, v38, v5
	s_nop 0
	v_cndmask_b32_e32 v36, 0, v4, vcc
	v_or_b32_e32 v4, 2, v6
	v_cmp_le_i32_e32 vcc, v4, v10
	v_or_b32_e32 v4, 3, v6
	v_add_u32_e32 v6, 16, v103
	v_cndmask_b32_e32 v37, 0, v5, vcc
	v_mul_f32_e32 v5, v39, v7
	v_cmp_le_i32_e32 vcc, v4, v10
	v_cvt_pk_bf16_f32 v4, v35, v36
	s_nop 1
	v_cndmask_b32_e32 v38, 0, v5, vcc
	v_cvt_pk_bf16_f32 v5, v37, v38
	ds_write_b64 v14, v[4:5] offset:16
	v_mov_b32_e32 v4, v169
	v_mov_b32_e32 v5, v170
	v_mov_b32_e32 v7, v171
	v_cmp_le_i32_e32 vcc, v6, v10
	s_and_saveexec_b64 s[10:11], vcc
	s_cbranch_execz .LBB0_1706
	v_mov_b32_e32 v13, v168
	s_nop 0
	v_add_f32_e32 v13, v11, v13
	v_mul_f32_e32 v13, 0x3fb8aa3b, v13
	v_exp_f32_e32 v13, v13
	s_nop 0
	v_mul_f32_e32 v13, v40, v13
.LBB0_1706:
	s_or_b64 exec, exec, s[10:11]
	s_nop 0
	v_add_f32_e32 v4, v11, v4
	v_mul_f32_e32 v4, 0x3fb8aa3b, v4
	v_add_f32_e32 v5, v11, v5
	v_exp_f32_e32 v4, v4
	v_mul_f32_e32 v5, 0x3fb8aa3b, v5
	v_exp_f32_e32 v5, v5
	s_nop 0
	v_add_f32_e32 v7, v11, v7
	v_mul_f32_e32 v7, 0x3fb8aa3b, v7
	v_exp_f32_e32 v7, v7
	v_mul_f32_e32 v4, v41, v4
	v_cmp_lt_i32_e32 vcc, v6, v10
	v_or_b32_e32 v39, 2, v6
	v_mul_f32_e32 v5, v42, v5
	v_cndmask_b32_e32 v4, 0, v4, vcc
	v_cmp_le_i32_e32 vcc, v39, v10
	v_add_u32_e32 v39, 24, v103
	s_nop 0
	v_cndmask_b32_e32 v40, 0, v5, vcc
	v_or_b32_e32 v5, 3, v6
	v_mul_f32_e32 v6, v43, v7
	v_cmp_le_i32_e32 vcc, v5, v10
	v_mov_b32_e32 v5, 0
	s_nop 0
	v_cndmask_b32_e32 v42, 0, v6, vcc
	v_cvt_pk_bf16_f32 v6, v13, v4
	v_cvt_pk_bf16_f32 v7, v40, v42
	ds_write_b64 v14, v[6:7] offset:32
	v_mov_b32_e32 v6, v173
	v_mov_b32_e32 v7, v174
	v_mov_b32_e32 v41, v175
	v_cmp_le_i32_e32 vcc, v39, v10
	s_and_saveexec_b64 s[10:11], vcc
	s_cbranch_execz .LBB0_1708
	v_mov_b32_e32 v5, v172
	s_nop 0
	v_add_f32_e32 v5, v11, v5
	v_mul_f32_e32 v5, 0x3fb8aa3b, v5
	v_exp_f32_e32 v5, v5
	s_nop 0
	v_mul_f32_e32 v5, v44, v5
.LBB0_1708:
	s_or_b64 exec, exec, s[10:11]
	v_add_f32_e32 v15, v32, v102
	v_add_f32_e32 v32, v33, v34
	v_add_f32_e32 v15, v32, v15
	v_add_f32_e32 v32, v36, v35
	v_add_f32_e32 v33, v37, v38
	v_add_f32_e32 v15, 0, v15
	v_add_f32_e32 v32, v33, v32
	v_add_f32_e32 v4, v4, v13
	v_add_f32_e32 v13, v40, v42
	v_add_f32_e32 v15, v15, v32
	v_add_f32_e32 v4, v13, v4
	v_add_f32_e32 v13, v15, v4
	s_nop 0
	v_add_f32_e32 v4, v11, v7
	v_mul_f32_e32 v4, 0x3fb8aa3b, v4
	s_nop 0
	v_add_f32_e32 v7, v11, v41
	v_add_f32_e32 v6, v11, v6
	v_exp_f32_e32 v4, v4
	v_mul_f32_e32 v7, 0x3fb8aa3b, v7
	v_mul_f32_e32 v6, 0x3fb8aa3b, v6
	v_exp_f32_e32 v7, v7
	v_exp_f32_e32 v6, v6
	v_mul_f32_e32 v32, v46, v4
	v_or_b32_e32 v4, 3, v39
	v_mul_f32_e32 v7, v47, v7
	v_cmp_le_i32_e32 vcc, v4, v10
	v_mul_f32_e32 v6, v45, v6
	v_or_b32_e32 v15, 2, v39
	v_cndmask_b32_e32 v4, 0, v7, vcc
	v_cmp_gt_i32_e32 vcc, v10, v39
	s_nop 1
	v_cndmask_b32_e32 v33, 0, v6, vcc
	v_cmp_le_i32_e32 vcc, v15, v10
	v_cvt_pk_bf16_f32 v34, v5, v33
	s_nop 1
	v_cndmask_b32_e32 v32, 0, v32, vcc
	v_pk_add_f32 v[6:7], v[32:33], v[4:5]
	v_cvt_pk_bf16_f32 v35, v32, v4
	ds_write_b64 v14, v[34:35] offset:48
	v_add_f32_e32 v6, v6, v7
	v_add_f32_e32 v6, v13, v6
	v_lshl_add_u32 v4, v100, 3, v12
	s_branch .LBB0_1698

.LBB0_1711:
	v_or_b32_e32 v4, s61, v101
	v_mad_u32_u24 v0, v4, s68, v0
	ds_read_b128 v[32:35], v0 offset:18432
	ds_read_b128 v[36:39], v2
	ds_read_b128 v[102:105], v2 offset:32
	ds_read_b128 v[106:109], v0 offset:18464
	v_add_u32_e32 v176, s61, v3
	v_lshl_add_u32 v176, v176, 2, v93
	ds_read_b128 v[160:163], v176
	ds_read_b128 v[164:167], v176 offset:32
	ds_read_b128 v[168:171], v176 offset:64
	ds_read_b128 v[172:175], v176 offset:96
	v_add_u32_e32 v15, s61, v3
	v_lshl_add_u32 v13, v15, 2, v93
	s_waitcnt lgkmcnt(6)
	v_mfma_f32_32x32x16_bf16 v[32:47], v[32:35], v[36:39], 0
	v_cmp_le_i32_e32 vcc, v15, v10
	v_mov_b32_e32 v14, 0
	s_waitcnt lgkmcnt(4)
	v_mfma_f32_32x32x16_bf16 v[32:47], v[106:109], v[102:105], v[32:47]
	ds_read_b128 v[102:105], v0 offset:18496
	ds_read_b128 v[106:109], v2 offset:64
	ds_read_b128 v[110:113], v0 offset:18528
	ds_read_b128 v[114:117], v2 offset:96
	s_waitcnt lgkmcnt(4)
	v_mov_b32_e32 v2, v161
	v_mov_b32_e32 v3, v162
	v_mov_b32_e32 v4, v163
	v_mov_b32_e32 v0, 0
	s_waitcnt lgkmcnt(2)
	v_mfma_f32_32x32x16_bf16 v[32:47], v[102:105], v[106:109], v[32:47]
	s_waitcnt lgkmcnt(0)
	v_mfma_f32_32x32x16_bf16 v[32:47], v[110:113], v[114:117], v[32:47]
	s_and_saveexec_b64 s[10:11], vcc
	s_cbranch_execz .LBB0_1713
	v_mov_b32_e32 v5, v160
	s_nop 0
	v_add_f32_e32 v5, v11, v5
	v_mul_f32_e32 v5, 0x3fb8aa3b, v5
	v_exp_f32_e32 v5, v5
	s_nop 4
	v_mul_f32_e32 v14, v32, v5
.LBB0_1713:
	s_or_b64 exec, exec, s[10:11]
	s_nop 0
	v_add_f32_e32 v2, v11, v2
	v_mul_f32_e32 v2, 0x3fb8aa3b, v2
	v_exp_f32_e32 v2, v2
	v_add_f32_e32 v3, v11, v3
	v_mul_f32_e32 v3, 0x3fb8aa3b, v3
	s_nop 0
	v_add_f32_e32 v4, v11, v4
	v_exp_f32_e32 v3, v3
	v_mul_f32_e32 v4, 0x3fb8aa3b, v4
	v_exp_f32_e32 v4, v4
	v_mul_f32_e32 v2, v33, v2
	v_cmp_lt_i32_e32 vcc, v15, v10
	v_mul_f32_e32 v3, v34, v3
	v_lshl_add_u32 v7, v15, 1, v12
	v_cndmask_b32_e32 v32, 0, v2, vcc
	v_or_b32_e32 v2, 2, v15
	v_cmp_le_i32_e32 vcc, v2, v10
	v_or_b32_e32 v2, 3, v15
	v_mov_b32_e32 v12, 0
	v_cndmask_b32_e32 v33, 0, v3, vcc
	v_mul_f32_e32 v3, v35, v4
	v_cmp_le_i32_e32 vcc, v2, v10
	v_cvt_pk_bf16_f32 v2, v14, v32
	v_add_u32_e32 v4, 8, v15
	s_nop 0
	v_cndmask_b32_e32 v34, 0, v3, vcc
	v_cvt_pk_bf16_f32 v3, v33, v34
	ds_write_b64 v7, v[2:3]
	v_mov_b32_e32 v2, v165
	v_mov_b32_e32 v3, v166
	v_mov_b32_e32 v5, v167
	v_cmp_le_i32_e32 vcc, v4, v10
	s_and_saveexec_b64 s[10:11], vcc
	s_cbranch_execz .LBB0_1715
	v_mov_b32_e32 v12, v164
	s_nop 0
	v_add_f32_e32 v12, v11, v12
	v_mul_f32_e32 v12, 0x3fb8aa3b, v12
	v_exp_f32_e32 v12, v12
	s_nop 0
	v_mul_f32_e32 v12, v36, v12
.LBB0_1715:
	s_or_b64 exec, exec, s[10:11]
	s_nop 0
	v_add_f32_e32 v2, v11, v2
	v_mul_f32_e32 v2, 0x3fb8aa3b, v2
	v_exp_f32_e32 v2, v2
	v_add_f32_e32 v3, v11, v3
	v_mul_f32_e32 v3, 0x3fb8aa3b, v3
	s_nop 0
	v_add_f32_e32 v5, v11, v5
	v_exp_f32_e32 v3, v3
	v_mul_f32_e32 v5, 0x3fb8aa3b, v5
	v_exp_f32_e32 v5, v5
	v_mul_f32_e32 v2, v37, v2
	v_cmp_lt_i32_e32 vcc, v4, v10
	v_mul_f32_e32 v3, v38, v3
	s_nop 0
	v_cndmask_b32_e32 v35, 0, v2, vcc
	v_or_b32_e32 v2, 2, v4
	v_cmp_le_i32_e32 vcc, v2, v10
	v_or_b32_e32 v2, 3, v4
	v_add_u32_e32 v4, 16, v15
	v_cndmask_b32_e32 v36, 0, v3, vcc
	v_mul_f32_e32 v3, v39, v5
	v_cmp_le_i32_e32 vcc, v2, v10
	v_cvt_pk_bf16_f32 v2, v12, v35
	s_nop 1
	v_cndmask_b32_e32 v37, 0, v3, vcc
	v_cvt_pk_bf16_f32 v3, v36, v37
	ds_write_b64 v7, v[2:3] offset:16
	v_mov_b32_e32 v2, v169
	v_mov_b32_e32 v3, v170
	v_mov_b32_e32 v5, v171
	v_cmp_le_i32_e32 vcc, v4, v10
	s_and_saveexec_b64 s[10:11], vcc
	s_cbranch_execz .LBB0_1717
	v_mov_b32_e32 v0, v168
	s_nop 0
	v_add_f32_e32 v0, v11, v0
	v_mul_f32_e32 v0, 0x3fb8aa3b, v0
	v_exp_f32_e32 v0, v0
	s_nop 0
	v_mul_f32_e32 v0, v40, v0
.LBB0_1717:
	s_or_b64 exec, exec, s[10:11]
	s_nop 0
	v_add_f32_e32 v2, v11, v2
	v_mul_f32_e32 v2, 0x3fb8aa3b, v2
	v_add_f32_e32 v3, v11, v3
	v_exp_f32_e32 v2, v2
	v_mul_f32_e32 v3, 0x3fb8aa3b, v3
	v_exp_f32_e32 v3, v3
	s_nop 0
	v_add_f32_e32 v5, v11, v5
	v_mul_f32_e32 v5, 0x3fb8aa3b, v5
	v_exp_f32_e32 v5, v5
	v_mul_f32_e32 v2, v41, v2
	v_cmp_lt_i32_e32 vcc, v4, v10
	v_or_b32_e32 v38, 2, v4
	v_mul_f32_e32 v3, v42, v3
	v_cndmask_b32_e32 v2, 0, v2, vcc
	v_cmp_le_i32_e32 vcc, v38, v10
	v_add_u32_e32 v15, 24, v15
	s_nop 0
	v_cndmask_b32_e32 v38, 0, v3, vcc
	v_or_b32_e32 v3, 3, v4
	v_mul_f32_e32 v4, v43, v5
	v_cmp_le_i32_e32 vcc, v3, v10
	v_mov_b32_e32 v3, 0
	s_nop 0
	v_cndmask_b32_e32 v40, 0, v4, vcc
	v_cvt_pk_bf16_f32 v4, v0, v2
	v_cvt_pk_bf16_f32 v5, v38, v40
	ds_write_b64 v7, v[4:5] offset:32
	v_mov_b32_e32 v4, v173
	v_mov_b32_e32 v5, v174
	v_mov_b32_e32 v39, v175
	v_cmp_le_i32_e32 vcc, v15, v10
	s_and_saveexec_b64 s[10:11], vcc
	s_cbranch_execz .LBB0_1719
	v_mov_b32_e32 v3, v172
	s_nop 0
	v_add_f32_e32 v3, v11, v3
	v_mul_f32_e32 v3, 0x3fb8aa3b, v3
	v_exp_f32_e32 v3, v3
	s_nop 0
	v_mul_f32_e32 v3, v44, v3
